# FFN-down phase: small per-XCD start delay (x/8 of 10 us) re-added on top of the split-K round
# baseline (speedup 1.0000x reference)
.LBB0_1252:
	s_abs_i32 s3, s10
	v_cvt_f32_u32_e32 v0, s3
	s_sub_i32 s11, 0, s3
	v_rcp_iflag_f32_e32 v0, v0
	s_nop 0
	v_mul_f32_e32 v0, 0x4f7ffffe, v0
	v_cvt_u32_f32_e32 v0, v0
	s_nop 0
	v_readfirstlane_b32 s14, v0
	s_mul_i32 s11, s11, s14
	s_mul_hi_u32 s11, s14, s11
	s_add_i32 s14, s14, s11
	s_mul_hi_u32 s11, s14, 0x440
	s_mul_i32 s11, s11, s3
	s_sub_i32 s11, 0x440, s11
	s_sub_i32 s14, s11, s3
	s_cmp_ge_u32 s11, s3
	s_cselect_b32 s11, s14, s11
	s_sub_i32 s14, s11, s3
	s_cmp_ge_u32 s11, s3
	s_cselect_b32 s3, s14, s11
	s_cmp_eq_u32 s3, 0
	s_cbranch_scc1 .LBB0_1250
	s_ashr_i32 s11, s10, 3
	s_abs_i32 s10, s11
	v_cvt_f32_u32_e32 v0, s10
	s_sub_i32 s16, 0, s10
	s_abs_i32 s14, s3
	s_xor_b32 s15, s3, s11
	v_rcp_iflag_f32_e32 v0, v0
	s_ashr_i32 s15, s15, 31
	v_mul_f32_e32 v0, 0x4f7ffffe, v0
	v_cvt_u32_f32_e32 v0, v0
	s_nop 0
	v_readfirstlane_b32 s17, v0
	s_mul_i32 s16, s16, s17
	s_mul_hi_u32 s16, s17, s16
	s_add_i32 s17, s17, s16
	s_mul_hi_u32 s16, s14, s17
	s_mul_i32 s17, s16, s10
	s_sub_i32 s14, s14, s17
	s_add_i32 s18, s16, 1
	s_sub_i32 s17, s14, s10
	s_cmp_ge_u32 s14, s10
	s_cselect_b32 s16, s18, s16
	s_cselect_b32 s14, s17, s14
	s_add_i32 s17, s16, 1
	s_cmp_ge_u32 s14, s10
	s_cselect_b32 s10, s17, s16
	s_xor_b32 s10, s10, s15
	s_sub_i32 s10, s10, s15
	s_mul_i32 s11, s10, s11
	s_sub_i32 s3, s3, s11
	s_cmp_lg_u32 s3, 0
	s_cbranch_scc1 .LBB0_1250
	s_and_b32 s2, s2, 7
	s_nop 0
	v_cvt_f32_i32_e32 v0, s2
	s_mov_b32 s2, 8
	v_cvt_f32_u32_e32 v1, s2
	v_mul_f32_e32 v0, 0x447a0000, v0
	v_div_scale_f32 v2, s[2:3], v1, v1, v0
	v_rcp_f32_e32 v3, v2
	v_div_scale_f32 v4, vcc, v0, v1, v0
	s_memrealtime s[2:3]
	v_fma_f32 v5, -v2, v3, 1.0
	v_fmac_f32_e32 v3, v5, v3
	v_mul_f32_e32 v5, v4, v3
	v_fma_f32 v6, -v2, v5, v4
	v_fmac_f32_e32 v5, v6, v3
	v_fma_f32 v2, -v2, v5, v4
	v_div_fmas_f32 v2, v2, v3, v5
	v_div_fixup_f32 v0, v2, v1, v0
	v_trunc_f32_e32 v0, v0
	v_mul_f32_e32 v1, 0x2f800000, v0
	v_floor_f32_e32 v1, v1
	v_fmac_f32_e32 v0, 0xcf800000, v1
	v_cvt_u32_f32_e32 v0, v0
	v_cvt_u32_f32_e32 v1, v1
	s_memrealtime s[10:11]
	s_waitcnt lgkmcnt(0)
	v_lshl_add_u64 v[0:1], s[2:3], 0, v[0:1]
	v_cmp_ge_u64_e32 vcc, s[10:11], v[0:1]
	s_cbranch_vccnz .LBB0_1250
